# mix item loop: static re-schedule (even vblocks scan + 4 window-attn items, odd vblocks 4 neighbourhood-attn items + ctx)
# baseline (speedup 1.0000x reference)
; DI void mix_phase(const Params& p, int layer, unsigned char* smem, unsigned char* smem_all, int bid, int nb, int rrank) {
;     ...
;   for (int it = 2 * rrank + (bid & 1); it < e6; it += nb) {
;     if (it < e0) scan_item(p, it);
;     else if (it < e1) {
;     } else if (it < e2) {
;     } else if (it < e3) {
;       const int j = it - e2, qb = j & 127, hq = (j >> 7) & 3, b = j >> 9;
;       const int t0 = qb * 128 + wave * 32;
;       attn64_wave<1>(p, layer, b, hq, b * SEQ + t0, t0, rpb_lds, smem + 8192 + wave * W64_BYTES);
;     } else if (it < e4) {
;       const int j = it - e3, qb = j & 127, hq = (j >> 7) & 3, b = j >> 9;
;       const int t0 = qb * 128 + wave * 32;
;       attn64_wave<0>(p, layer, b, hq, b * SEQ + t0, t0, rpb_lds, smem + 8192 + wave * W64_BYTES);
;     } else if (it < e5) {
;       const int j = it - e4, qb = j & 1, hq = (j >> 1) & 3, b = j >> 3;
;       attn64_wave<3>(p, layer, b, hq, TL + b * CTX + qb * 128 + wave * 32, 0, rpb_lds, smem + 8192 + wave * W64_BYTES);
;     } else {
;       const int j = it - e5, qb = j & 1, hq = (j >> 1) & 3, b = j >> 3;
;       attn64_wave<2>(p, layer, b, hq, TL + b * CTX + qb * 128 + wave * 32, 0, rpb_lds, smem + 8192 + wave * W64_BYTES);
;     }
;   }
.LBB0_319:
	s_or_b64 exec, exec, s[2:3]
	s_and_b64 s[2:3], s[42:43], exec
	s_cselect_b32 s2, 16, 0
	s_or_b32 s3, s2, 0xd00
	s_add_i32 s21, s3, s2
	v_writelane_b32 v254, s3, 60
	s_add_i32 s22, s21, s2
	v_readlane_b32 s3, v253, 49
	v_writelane_b32 v254, s22, 61
	s_cmp_ge_i32 s3, s22
	s_waitcnt lgkmcnt(0)
	s_barrier
	s_cbranch_scc1 .LBB0_436
	v_writelane_b32 v254, s21, 62
	v_ashrrev_i32_e32 v0, 6, v238
	s_movk_i32 s3, 0x2600
	v_readlane_b32 s24, v254, 52
	s_waitcnt vmcnt(16)
	v_lshlrev_b32_e32 v152, 5, v0
	v_mul_lo_u32 v0, v0, s3
	s_lshl_b32 s3, s24, 2
	v_readlane_b32 s25, v254, 53
	v_writelane_b32 v254, s3, 63
	s_lshl_b32 s22, s24, 6
	v_readlane_b32 s40, v254, 18
	s_or_b32 s27, s2, 0x500
	s_or_b32 s48, s2, 0x900
	s_lshl_b64 s[24:25], s[22:23], 2
	v_readlane_b32 s42, v254, 20
	v_readlane_b32 s43, v254, 21
	s_add_u32 s28, s42, s24
	s_addc_u32 s29, s43, s25
	v_readlane_b32 s44, v254, 22
	v_writelane_b32 v255, s28, 0
	v_readlane_b32 s45, v254, 23
	v_readlane_b32 s21, v253, 44
	v_writelane_b32 v255, s29, 1
	s_add_u32 s28, s44, s24
	s_addc_u32 s29, s45, s25
	v_writelane_b32 v255, s28, 2
	v_add_u32_e32 v153, s90, v0
	v_and_b32_e32 v154, 32, v152
	v_writelane_b32 v255, s29, 3
	v_readlane_b32 s28, v254, 6
	v_readlane_b32 s29, v254, 7
	s_add_u32 s28, s28, s24
	v_readlane_b32 s30, v254, 8
	s_addc_u32 s29, s29, s25
	v_readlane_b32 s31, v254, 9
	v_writelane_b32 v255, s28, 4
	s_add_u32 s24, s30, s24
	s_addc_u32 s25, s31, s25
	v_writelane_b32 v255, s29, 5
	v_writelane_b32 v255, s24, 6
	s_lshl_b32 s3, s2, 1
	s_sub_i32 s21, s21, s3
	v_writelane_b32 v255, s25, 7
	v_readlane_b32 s3, v253, 50
	s_sub_i32 s2, s3, s2
	v_writelane_b32 v255, s27, 8
	s_lshl_b32 s38, s2, 7
	v_readlane_b32 s39, v253, 57
	v_readlane_b32 s40, v253, 49
	v_writelane_b32 v255, s48, 9
	v_readlane_b32 s41, v254, 19
	v_readlane_b32 s46, v254, 24
	v_readlane_b32 s47, v254, 25
	s_lshr_b32 s3, s40, 1
	s_and_b32 s2, s40, 1
	s_cmp_eq_u32 s2, 0
	s_cselect_b32 s2, 0, s48
	s_add_i32 s2, s2, s3
	s_sub_i32 s2, s2, s40
	s_add_i32 s40, s40, s2
	s_add_i32 s21, s21, s2
	s_lshl_b32 s3, s2, 7
	s_add_i32 s38, s38, s3
	s_lshl_b32 s3, s2, 8
	s_add_i32 s39, s39, s3
	s_branch .LBB0_322
.LBB0_321:
	v_readlane_b32 s98, v255, 9
	v_readlane_b32 s99, v254, 60
	s_cmpk_gt_i32 s40, 0xff
	s_cbranch_scc1 .Lmix_ns
	v_readlane_b32 s2, v255, 8
	s_branch .Lmix_adv
.Lmix_ns:
	s_cmp_ge_i32 s40, s99
	s_cbranch_scc1 .LBB0_435
	s_movk_i32 s2, 0x100
	s_add_i32 s100, s40, 0x100
	s_cmp_lt_i32 s40, s98
	s_cbranch_scc0 .Lmix_c
	s_cmp_lt_i32 s100, s98
	s_cbranch_scc1 .Lmix_adv
	s_branch .LBB0_435
.Lmix_c:
	s_cmp_lt_i32 s100, s99
	s_cbranch_scc1 .Lmix_adv
	s_sub_i32 s100, s40, s98
	s_and_b32 s100, s100, 0xff
	v_readlane_b32 s101, v254, 62
	s_sub_i32 s101, s101, s99
	s_lshl_b32 s101, s101, 1
	s_cmp_lt_i32 s100, s101
	s_cbranch_scc0 .LBB0_435
	s_add_i32 s100, s100, s99
	s_sub_i32 s2, s100, s40
.Lmix_adv:
	s_add_i32 s40, s40, s2
	s_add_i32 s21, s21, s2
	s_lshl_b32 s3, s2, 7
	s_add_i32 s38, s38, s3
	s_lshl_b32 s3, s2, 8
	s_add_i32 s39, s39, s3
